# hand EpiRes epilogue (all residual loads up front, permlane row-sum) on top of v078
# baseline (speedup 1.0000x reference)
; #define ER_LOAD(q) do { _Pragma("unroll") for (int bj = 0; bj < 2; ++bj) t[(q) & 3][bj] = *(const u32x4*)(base + ER_OFF(q, bj)); } while (0)
; #define ER_ADD(q) do { _Pragma("unroll") for (int bj = 0; bj < 2; ++bj) { f32x4& a0 = acc[(q) >> 2][bj][(q) & 3][0]; f32x4& a1 = acc[(q) >> 2][bj][(q) & 3][1]; const u32x4 p = t[(q) & 3][bj]; \
;             a0[0] += bf_lo(p.x); a0[1] += bf_hi(p.x); a0[2] += bf_lo(p.y); a0[3] += bf_hi(p.y); a1[0] += bf_lo(p.z); a1[1] += bf_hi(p.z); a1[2] += bf_lo(p.w); a1[3] += bf_hi(p.w); } } while (0)
;     __device__ __forceinline__ void operator()(f32x4 (&acc)[2][2][4][2], const Unit& u, int wr, int wc, int fr, int fq) const {
;         const int row0 = u.pm * BM + wr * 64 + fr, col0 = u.pn * BM + wc * 32 + 8 * fq; const unsigned off0 = (unsigned)row0 * 1024u + (unsigned)col0;
;         u32x4 t[4][2];
;     ...
; #pragma unroll
;         for (int q = 0; q < 4; ++q) ER_LOAD(q);
; #pragma unroll
;         for (int q = 0; q < 4; ++q) ER_ADD(q);
; #pragma unroll
;         for (int q = 4; q < 8; ++q) ER_LOAD(q);
; #pragma unroll
;         for (int q = 0; q < 4; ++q) ER_STORE(q);
; #pragma unroll
;         for (int q = 4; q < 8; ++q) { ER_ADD(q); ER_STORE(q); }
.LBB0_276:
	v_mov_b32_e32 v246, 0
	v_mov_b32_e32 v247, 0
	v_lshrrev_b32_e32 v240, 8, v170
	v_and_b32_e32 v241, 15, v170
	v_lshl_add_u32 v240, v240, 6, v241
	s_lshl_b32 s98, s67, 8
	v_add_u32_e32 v240, s98, v240
	v_bfe_u32 v241, v170, 6, 2
	v_bfe_u32 v242, v170, 4, 2
	v_cmp_eq_u32_e32 vcc, 0, v242
	v_lshlrev_b32_e32 v241, 5, v241
	v_lshl_or_b32 v241, v242, 3, v241
	s_lshl_b32 s98, s66, 8
	v_add_u32_e32 v241, s98, v241
	v_lshl_add_u32 v241, v240, 10, v241
	v_lshlrev_b32_e32 v216, 1, v241
	v_mov_b32_e32 v217, 0
	v_lshl_add_u64 v[218:219], v[216:217], 0, s[42:43]
	v_lshl_add_u64 v[216:217], v[216:217], 0, v[176:177]
	v_lshlrev_b32_e32 v220, 3, v240
	v_mov_b32_e32 v221, 0
	v_lshl_add_u64 v[220:221], v[220:221], 0, s[40:41]
	s_mov_b32 s98, 0x8000
	s_mov_b32 s99, 0
	global_load_dwordx4 v[128:131], v[216:217], off
	global_load_dwordx4 v[132:135], v[216:217], off offset:256
	v_lshl_add_u64 v[216:217], v[216:217], 0, s[98:99]
	global_load_dwordx4 v[136:139], v[216:217], off
	global_load_dwordx4 v[140:143], v[216:217], off offset:256
	v_lshl_add_u64 v[216:217], v[216:217], 0, s[98:99]
	global_load_dwordx4 v[144:147], v[216:217], off
	global_load_dwordx4 v[148:151], v[216:217], off offset:256
	v_lshl_add_u64 v[216:217], v[216:217], 0, s[98:99]
	global_load_dwordx4 v[152:155], v[216:217], off
	global_load_dwordx4 v[156:159], v[216:217], off offset:256
	v_lshl_add_u64 v[216:217], v[216:217], 0, s[98:99]
	v_lshl_add_u64 v[216:217], v[216:217], 0, s[98:99]
	v_lshl_add_u64 v[216:217], v[216:217], 0, s[98:99]
	v_lshl_add_u64 v[216:217], v[216:217], 0, s[98:99]
	v_lshl_add_u64 v[216:217], v[216:217], 0, s[98:99]
	global_load_dwordx4 v[160:163], v[216:217], off
	global_load_dwordx4 v[164:167], v[216:217], off offset:256
	v_lshl_add_u64 v[216:217], v[216:217], 0, s[98:99]
	global_load_dwordx4 v[192:195], v[216:217], off
	global_load_dwordx4 v[196:199], v[216:217], off offset:256
	v_lshl_add_u64 v[216:217], v[216:217], 0, s[98:99]
	global_load_dwordx4 v[200:203], v[216:217], off
	global_load_dwordx4 v[204:207], v[216:217], off offset:256
	v_lshl_add_u64 v[216:217], v[216:217], 0, s[98:99]
	global_load_dwordx4 v[208:211], v[216:217], off
	global_load_dwordx4 v[212:215], v[216:217], off offset:256
	s_waitcnt vmcnt(14)
	v_lshlrev_b32_e32 v241, 16, v128
	v_and_b32_e32 v242, 0xffff0000, v128
	v_add_f32_e32 v124, v124, v241
	v_add_f32_e32 v125, v125, v242
	v_lshlrev_b32_e32 v241, 16, v129
	v_and_b32_e32 v242, 0xffff0000, v129
	v_add_f32_e32 v126, v126, v241
	v_add_f32_e32 v127, v127, v242
	v_lshlrev_b32_e32 v241, 16, v130
	v_and_b32_e32 v242, 0xffff0000, v130
	v_add_f32_e32 v120, v120, v241
	v_add_f32_e32 v121, v121, v242
	v_lshlrev_b32_e32 v241, 16, v131
	v_and_b32_e32 v242, 0xffff0000, v131
	v_add_f32_e32 v122, v122, v241
	v_add_f32_e32 v123, v123, v242
	v_cvt_pk_bf16_f32 v124, v124, v125
	v_cvt_pk_bf16_f32 v125, v126, v127
	v_cvt_pk_bf16_f32 v126, v120, v121
	v_cvt_pk_bf16_f32 v127, v122, v123
	global_store_dwordx4 v[218:219], v[124:127], off
	v_and_b32_e32 v241, 0xffff0000, v124
	v_lshlrev_b32_e32 v242, 16, v124
	v_mul_f32_e32 v241, v241, v241
	v_fmac_f32_e32 v241, v242, v242
	v_mov_b32_e32 v240, v241
	v_and_b32_e32 v241, 0xffff0000, v125
	v_lshlrev_b32_e32 v242, 16, v125
	v_mul_f32_e32 v241, v241, v241
	v_fmac_f32_e32 v241, v242, v242
	v_add_f32_e32 v240, v240, v241
	v_and_b32_e32 v241, 0xffff0000, v126
	v_lshlrev_b32_e32 v242, 16, v126
	v_mul_f32_e32 v241, v241, v241
	v_fmac_f32_e32 v241, v242, v242
	v_add_f32_e32 v240, v240, v241
	v_and_b32_e32 v241, 0xffff0000, v127
	v_lshlrev_b32_e32 v242, 16, v127
	v_mul_f32_e32 v241, v241, v241
	v_fmac_f32_e32 v241, v242, v242
	v_add_f32_e32 v240, v240, v241
	v_lshlrev_b32_e32 v241, 16, v132
	v_and_b32_e32 v242, 0xffff0000, v132
	v_add_f32_e32 v116, v116, v241
	v_add_f32_e32 v117, v117, v242
	v_lshlrev_b32_e32 v241, 16, v133
	v_and_b32_e32 v242, 0xffff0000, v133
	v_add_f32_e32 v118, v118, v241
	v_add_f32_e32 v119, v119, v242
	v_lshlrev_b32_e32 v241, 16, v134
	v_and_b32_e32 v242, 0xffff0000, v134
	v_add_f32_e32 v112, v112, v241
	v_add_f32_e32 v113, v113, v242
	v_lshlrev_b32_e32 v241, 16, v135
	v_and_b32_e32 v242, 0xffff0000, v135
	v_add_f32_e32 v114, v114, v241
	v_add_f32_e32 v115, v115, v242
	v_cvt_pk_bf16_f32 v116, v116, v117
	v_cvt_pk_bf16_f32 v117, v118, v119
	v_cvt_pk_bf16_f32 v118, v112, v113
	v_cvt_pk_bf16_f32 v119, v114, v115
	global_store_dwordx4 v[218:219], v[116:119], off offset:256
	v_and_b32_e32 v241, 0xffff0000, v116
	v_lshlrev_b32_e32 v242, 16, v116
	v_mul_f32_e32 v241, v241, v241
	v_fmac_f32_e32 v241, v242, v242
	v_add_f32_e32 v240, v240, v241
	v_and_b32_e32 v241, 0xffff0000, v117
	v_lshlrev_b32_e32 v242, 16, v117
	v_mul_f32_e32 v241, v241, v241
	v_fmac_f32_e32 v241, v242, v242
	v_add_f32_e32 v240, v240, v241
	v_and_b32_e32 v241, 0xffff0000, v118
	v_lshlrev_b32_e32 v242, 16, v118
	v_mul_f32_e32 v241, v241, v241
	v_fmac_f32_e32 v241, v242, v242
	v_add_f32_e32 v240, v240, v241
	v_and_b32_e32 v241, 0xffff0000, v119
	v_lshlrev_b32_e32 v242, 16, v119
	v_mul_f32_e32 v241, v241, v241
	v_fmac_f32_e32 v241, v242, v242
	v_add_f32_e32 v240, v240, v241
	v_lshl_add_u64 v[218:219], v[218:219], 0, s[98:99]
	v_mov_b32_e32 v244, v240
	s_nop 1
	v_permlane16_swap_b32_e32 v244, v240
	s_nop 1
	v_add_f32_e32 v244, v240, v244
	v_mov_b32_e32 v245, v244
	s_nop 1
	v_permlane32_swap_b32_e32 v245, v244
	s_nop 1
	v_add_f32_e32 v244, v244, v245
	v_mul_f32_e32 v244, 0x49800000, v244
	v_trunc_f32_e32 v244, v244
	v_mul_f32_e32 v245, 0x2f800000, v244
	v_floor_f32_e32 v245, v245
	v_fmac_f32_e32 v244, 0xcf800000, v245
	v_cvt_u32_f32_e32 v245, v245
	v_cvt_u32_f32_e32 v244, v244
	s_and_saveexec_b64 s[10:11], vcc
	global_atomic_add_x2 v[220:221], v[244:245], off
	s_or_b64 exec, exec, s[10:11]
	s_waitcnt vmcnt(15)
; #define ER_LOAD(q) do { _Pragma("unroll") for (int bj = 0; bj < 2; ++bj) t[(q) & 3][bj] = *(const u32x4*)(base + ER_OFF(q, bj)); } while (0)
; #define ER_ADD(q) do { _Pragma("unroll") for (int bj = 0; bj < 2; ++bj) { f32x4& a0 = acc[(q) >> 2][bj][(q) & 3][0]; f32x4& a1 = acc[(q) >> 2][bj][(q) & 3][1]; const u32x4 p = t[(q) & 3][bj]; \
;             a0[0] += bf_lo(p.x); a0[1] += bf_hi(p.x); a0[2] += bf_lo(p.y); a0[3] += bf_hi(p.y); a1[0] += bf_lo(p.z); a1[1] += bf_hi(p.z); a1[2] += bf_lo(p.w); a1[3] += bf_hi(p.w); } } while (0)
;     __device__ __forceinline__ void operator()(f32x4 (&acc)[2][2][4][2], const Unit& u, int wr, int wc, int fr, int fq) const {
;         const int row0 = u.pm * BM + wr * 64 + fr, col0 = u.pn * BM + wc * 32 + 8 * fq; const unsigned off0 = (unsigned)row0 * 1024u + (unsigned)col0;
;         u32x4 t[4][2];
;     ...
; #pragma unroll
;         for (int q = 0; q < 4; ++q) ER_LOAD(q);
; #pragma unroll
;         for (int q = 0; q < 4; ++q) ER_ADD(q);
; #pragma unroll
;         for (int q = 4; q < 8; ++q) ER_LOAD(q);
; #pragma unroll
;         for (int q = 0; q < 4; ++q) ER_STORE(q);
	v_lshlrev_b32_e32 v241, 16, v136
	v_and_b32_e32 v242, 0xffff0000, v136
	v_add_f32_e32 v108, v108, v241
	v_add_f32_e32 v109, v109, v242
	v_lshlrev_b32_e32 v241, 16, v137
	v_and_b32_e32 v242, 0xffff0000, v137
	v_add_f32_e32 v110, v110, v241
	v_add_f32_e32 v111, v111, v242
	v_lshlrev_b32_e32 v241, 16, v138
	v_and_b32_e32 v242, 0xffff0000, v138
	v_add_f32_e32 v104, v104, v241
	v_add_f32_e32 v105, v105, v242
	v_lshlrev_b32_e32 v241, 16, v139
	v_and_b32_e32 v242, 0xffff0000, v139
	v_add_f32_e32 v106, v106, v241
	v_add_f32_e32 v107, v107, v242
	v_cvt_pk_bf16_f32 v108, v108, v109
	v_cvt_pk_bf16_f32 v109, v110, v111
	v_cvt_pk_bf16_f32 v110, v104, v105
	v_cvt_pk_bf16_f32 v111, v106, v107
	global_store_dwordx4 v[218:219], v[108:111], off
	v_and_b32_e32 v241, 0xffff0000, v108
	v_lshlrev_b32_e32 v242, 16, v108
	v_mul_f32_e32 v241, v241, v241
	v_fmac_f32_e32 v241, v242, v242
	v_mov_b32_e32 v240, v241
	v_and_b32_e32 v241, 0xffff0000, v109
	v_lshlrev_b32_e32 v242, 16, v109
	v_mul_f32_e32 v241, v241, v241
	v_fmac_f32_e32 v241, v242, v242
	v_add_f32_e32 v240, v240, v241
	v_and_b32_e32 v241, 0xffff0000, v110
	v_lshlrev_b32_e32 v242, 16, v110
	v_mul_f32_e32 v241, v241, v241
	v_fmac_f32_e32 v241, v242, v242
	v_add_f32_e32 v240, v240, v241
	v_and_b32_e32 v241, 0xffff0000, v111
	v_lshlrev_b32_e32 v242, 16, v111
	v_mul_f32_e32 v241, v241, v241
	v_fmac_f32_e32 v241, v242, v242
	v_add_f32_e32 v240, v240, v241
	v_lshlrev_b32_e32 v241, 16, v140
	v_and_b32_e32 v242, 0xffff0000, v140
	v_add_f32_e32 v100, v100, v241
	v_add_f32_e32 v101, v101, v242
	v_lshlrev_b32_e32 v241, 16, v141
	v_and_b32_e32 v242, 0xffff0000, v141
	v_add_f32_e32 v102, v102, v241
	v_add_f32_e32 v103, v103, v242
	v_lshlrev_b32_e32 v241, 16, v142
	v_and_b32_e32 v242, 0xffff0000, v142
	v_add_f32_e32 v96, v96, v241
	v_add_f32_e32 v97, v97, v242
	v_lshlrev_b32_e32 v241, 16, v143
	v_and_b32_e32 v242, 0xffff0000, v143
	v_add_f32_e32 v98, v98, v241
	v_add_f32_e32 v99, v99, v242
	v_cvt_pk_bf16_f32 v100, v100, v101
	v_cvt_pk_bf16_f32 v101, v102, v103
	v_cvt_pk_bf16_f32 v102, v96, v97
	v_cvt_pk_bf16_f32 v103, v98, v99
	global_store_dwordx4 v[218:219], v[100:103], off offset:256
	v_and_b32_e32 v241, 0xffff0000, v100
	v_lshlrev_b32_e32 v242, 16, v100
	v_mul_f32_e32 v241, v241, v241
	v_fmac_f32_e32 v241, v242, v242
	v_add_f32_e32 v240, v240, v241
	v_and_b32_e32 v241, 0xffff0000, v101
	v_lshlrev_b32_e32 v242, 16, v101
	v_mul_f32_e32 v241, v241, v241
	v_fmac_f32_e32 v241, v242, v242
	v_add_f32_e32 v240, v240, v241
	v_and_b32_e32 v241, 0xffff0000, v102
	v_lshlrev_b32_e32 v242, 16, v102
	v_mul_f32_e32 v241, v241, v241
	v_fmac_f32_e32 v241, v242, v242
	v_add_f32_e32 v240, v240, v241
	v_and_b32_e32 v241, 0xffff0000, v103
	v_lshlrev_b32_e32 v242, 16, v103
	v_mul_f32_e32 v241, v241, v241
	v_fmac_f32_e32 v241, v242, v242
	v_add_f32_e32 v240, v240, v241
	v_lshl_add_u64 v[218:219], v[218:219], 0, s[98:99]
	v_mov_b32_e32 v244, v240
	s_nop 1
	v_permlane16_swap_b32_e32 v244, v240
	s_nop 1
	v_add_f32_e32 v244, v240, v244
	v_mov_b32_e32 v245, v244
	s_nop 1
	v_permlane32_swap_b32_e32 v245, v244
	s_nop 1
	v_add_f32_e32 v244, v244, v245
	v_mul_f32_e32 v244, 0x49800000, v244
	v_trunc_f32_e32 v244, v244
	v_mul_f32_e32 v245, 0x2f800000, v244
	v_floor_f32_e32 v245, v245
	v_fmac_f32_e32 v244, 0xcf800000, v245
	v_cvt_u32_f32_e32 v245, v245
	v_cvt_u32_f32_e32 v244, v244
	s_and_saveexec_b64 s[10:11], vcc
	global_atomic_add_x2 v[220:221], v[244:245], off offset:128
	s_or_b64 exec, exec, s[10:11]
	s_waitcnt vmcnt(16)
	v_lshlrev_b32_e32 v241, 16, v144
	v_and_b32_e32 v242, 0xffff0000, v144
	v_add_f32_e32 v92, v92, v241
	v_add_f32_e32 v93, v93, v242
	v_lshlrev_b32_e32 v241, 16, v145
	v_and_b32_e32 v242, 0xffff0000, v145
	v_add_f32_e32 v94, v94, v241
	v_add_f32_e32 v95, v95, v242
	v_lshlrev_b32_e32 v241, 16, v146
	v_and_b32_e32 v242, 0xffff0000, v146
	v_add_f32_e32 v88, v88, v241
	v_add_f32_e32 v89, v89, v242
	v_lshlrev_b32_e32 v241, 16, v147
	v_and_b32_e32 v242, 0xffff0000, v147
	v_add_f32_e32 v90, v90, v241
	v_add_f32_e32 v91, v91, v242
	v_cvt_pk_bf16_f32 v92, v92, v93
	v_cvt_pk_bf16_f32 v93, v94, v95
	v_cvt_pk_bf16_f32 v94, v88, v89
	v_cvt_pk_bf16_f32 v95, v90, v91
	global_store_dwordx4 v[218:219], v[92:95], off
	v_and_b32_e32 v241, 0xffff0000, v92
	v_lshlrev_b32_e32 v242, 16, v92
	v_mul_f32_e32 v241, v241, v241
	v_fmac_f32_e32 v241, v242, v242
	v_mov_b32_e32 v240, v241
	v_and_b32_e32 v241, 0xffff0000, v93
	v_lshlrev_b32_e32 v242, 16, v93
	v_mul_f32_e32 v241, v241, v241
	v_fmac_f32_e32 v241, v242, v242
	v_add_f32_e32 v240, v240, v241
	v_and_b32_e32 v241, 0xffff0000, v94
	v_lshlrev_b32_e32 v242, 16, v94
	v_mul_f32_e32 v241, v241, v241
	v_fmac_f32_e32 v241, v242, v242
	v_add_f32_e32 v240, v240, v241
	v_and_b32_e32 v241, 0xffff0000, v95
	v_lshlrev_b32_e32 v242, 16, v95
	v_mul_f32_e32 v241, v241, v241
	v_fmac_f32_e32 v241, v242, v242
	v_add_f32_e32 v240, v240, v241
	v_lshlrev_b32_e32 v241, 16, v148
	v_and_b32_e32 v242, 0xffff0000, v148
	v_add_f32_e32 v84, v84, v241
	v_add_f32_e32 v85, v85, v242
	v_lshlrev_b32_e32 v241, 16, v149
	v_and_b32_e32 v242, 0xffff0000, v149
	v_add_f32_e32 v86, v86, v241
	v_add_f32_e32 v87, v87, v242
	v_lshlrev_b32_e32 v241, 16, v150
	v_and_b32_e32 v242, 0xffff0000, v150
	v_add_f32_e32 v80, v80, v241
	v_add_f32_e32 v81, v81, v242
	v_lshlrev_b32_e32 v241, 16, v151
	v_and_b32_e32 v242, 0xffff0000, v151
	v_add_f32_e32 v82, v82, v241
	v_add_f32_e32 v83, v83, v242
	v_cvt_pk_bf16_f32 v84, v84, v85
	v_cvt_pk_bf16_f32 v85, v86, v87
	v_cvt_pk_bf16_f32 v86, v80, v81
	v_cvt_pk_bf16_f32 v87, v82, v83
	global_store_dwordx4 v[218:219], v[84:87], off offset:256
	v_and_b32_e32 v241, 0xffff0000, v84
	v_lshlrev_b32_e32 v242, 16, v84
	v_mul_f32_e32 v241, v241, v241
	v_fmac_f32_e32 v241, v242, v242
	v_add_f32_e32 v240, v240, v241
	v_and_b32_e32 v241, 0xffff0000, v85
	v_lshlrev_b32_e32 v242, 16, v85
	v_mul_f32_e32 v241, v241, v241
	v_fmac_f32_e32 v241, v242, v242
	v_add_f32_e32 v240, v240, v241
	v_and_b32_e32 v241, 0xffff0000, v86
	v_lshlrev_b32_e32 v242, 16, v86
	v_mul_f32_e32 v241, v241, v241
	v_fmac_f32_e32 v241, v242, v242
	v_add_f32_e32 v240, v240, v241
	v_and_b32_e32 v241, 0xffff0000, v87
	v_lshlrev_b32_e32 v242, 16, v87
	v_mul_f32_e32 v241, v241, v241
	v_fmac_f32_e32 v241, v242, v242
	v_add_f32_e32 v240, v240, v241
	v_lshl_add_u64 v[218:219], v[218:219], 0, s[98:99]
	v_mov_b32_e32 v244, v240
	s_nop 1
	v_permlane16_swap_b32_e32 v244, v240
	s_nop 1
	v_add_f32_e32 v244, v240, v244
	v_mov_b32_e32 v245, v244
	s_nop 1
	v_permlane32_swap_b32_e32 v245, v244
	s_nop 1
	v_add_f32_e32 v244, v244, v245
	v_mul_f32_e32 v244, 0x49800000, v244
	v_trunc_f32_e32 v244, v244
	v_mul_f32_e32 v245, 0x2f800000, v244
	v_floor_f32_e32 v245, v245
	v_fmac_f32_e32 v244, 0xcf800000, v245
	v_cvt_u32_f32_e32 v245, v245
	v_cvt_u32_f32_e32 v244, v244
	s_and_saveexec_b64 s[10:11], vcc
	global_atomic_add_x2 v[220:221], v[244:245], off offset:256
	s_or_b64 exec, exec, s[10:11]
	s_waitcnt vmcnt(17)
; #define ER_LOAD(q) do { _Pragma("unroll") for (int bj = 0; bj < 2; ++bj) t[(q) & 3][bj] = *(const u32x4*)(base + ER_OFF(q, bj)); } while (0)
; #define ER_ADD(q) do { _Pragma("unroll") for (int bj = 0; bj < 2; ++bj) { f32x4& a0 = acc[(q) >> 2][bj][(q) & 3][0]; f32x4& a1 = acc[(q) >> 2][bj][(q) & 3][1]; const u32x4 p = t[(q) & 3][bj]; \
;             a0[0] += bf_lo(p.x); a0[1] += bf_hi(p.x); a0[2] += bf_lo(p.y); a0[3] += bf_hi(p.y); a1[0] += bf_lo(p.z); a1[1] += bf_hi(p.z); a1[2] += bf_lo(p.w); a1[3] += bf_hi(p.w); } } while (0)
;     __device__ __forceinline__ void operator()(f32x4 (&acc)[2][2][4][2], const Unit& u, int wr, int wc, int fr, int fq) const {
;         const int row0 = u.pm * BM + wr * 64 + fr, col0 = u.pn * BM + wc * 32 + 8 * fq; const unsigned off0 = (unsigned)row0 * 1024u + (unsigned)col0;
;         u32x4 t[4][2];
;     ...
; #pragma unroll
;         for (int q = 0; q < 4; ++q) ER_LOAD(q);
; #pragma unroll
;         for (int q = 0; q < 4; ++q) ER_ADD(q);
; #pragma unroll
;         for (int q = 4; q < 8; ++q) ER_LOAD(q);
; #pragma unroll
;         for (int q = 0; q < 4; ++q) ER_STORE(q);
; #pragma unroll
;         for (int q = 4; q < 8; ++q) { ER_ADD(q); ER_STORE(q); }
	v_lshlrev_b32_e32 v241, 16, v152
	v_and_b32_e32 v242, 0xffff0000, v152
	v_add_f32_e32 v76, v76, v241
	v_add_f32_e32 v77, v77, v242
	v_lshlrev_b32_e32 v241, 16, v153
	v_and_b32_e32 v242, 0xffff0000, v153
	v_add_f32_e32 v78, v78, v241
	v_add_f32_e32 v79, v79, v242
	v_lshlrev_b32_e32 v241, 16, v154
	v_and_b32_e32 v242, 0xffff0000, v154
	v_add_f32_e32 v72, v72, v241
	v_add_f32_e32 v73, v73, v242
	v_lshlrev_b32_e32 v241, 16, v155
	v_and_b32_e32 v242, 0xffff0000, v155
	v_add_f32_e32 v74, v74, v241
	v_add_f32_e32 v75, v75, v242
	v_cvt_pk_bf16_f32 v76, v76, v77
	v_cvt_pk_bf16_f32 v77, v78, v79
	v_cvt_pk_bf16_f32 v78, v72, v73
	v_cvt_pk_bf16_f32 v79, v74, v75
	global_store_dwordx4 v[218:219], v[76:79], off
	v_and_b32_e32 v241, 0xffff0000, v76
	v_lshlrev_b32_e32 v242, 16, v76
	v_mul_f32_e32 v241, v241, v241
	v_fmac_f32_e32 v241, v242, v242
	v_mov_b32_e32 v240, v241
	v_and_b32_e32 v241, 0xffff0000, v77
	v_lshlrev_b32_e32 v242, 16, v77
	v_mul_f32_e32 v241, v241, v241
	v_fmac_f32_e32 v241, v242, v242
	v_add_f32_e32 v240, v240, v241
	v_and_b32_e32 v241, 0xffff0000, v78
	v_lshlrev_b32_e32 v242, 16, v78
	v_mul_f32_e32 v241, v241, v241
	v_fmac_f32_e32 v241, v242, v242
	v_add_f32_e32 v240, v240, v241
	v_and_b32_e32 v241, 0xffff0000, v79
	v_lshlrev_b32_e32 v242, 16, v79
	v_mul_f32_e32 v241, v241, v241
	v_fmac_f32_e32 v241, v242, v242
	v_add_f32_e32 v240, v240, v241
	v_lshlrev_b32_e32 v241, 16, v156
	v_and_b32_e32 v242, 0xffff0000, v156
	v_add_f32_e32 v68, v68, v241
	v_add_f32_e32 v69, v69, v242
	v_lshlrev_b32_e32 v241, 16, v157
	v_and_b32_e32 v242, 0xffff0000, v157
	v_add_f32_e32 v70, v70, v241
	v_add_f32_e32 v71, v71, v242
	v_lshlrev_b32_e32 v241, 16, v158
	v_and_b32_e32 v242, 0xffff0000, v158
	v_add_f32_e32 v64, v64, v241
	v_add_f32_e32 v65, v65, v242
	v_lshlrev_b32_e32 v241, 16, v159
	v_and_b32_e32 v242, 0xffff0000, v159
	v_add_f32_e32 v66, v66, v241
	v_add_f32_e32 v67, v67, v242
	v_cvt_pk_bf16_f32 v68, v68, v69
	v_cvt_pk_bf16_f32 v69, v70, v71
	v_cvt_pk_bf16_f32 v70, v64, v65
	v_cvt_pk_bf16_f32 v71, v66, v67
	global_store_dwordx4 v[218:219], v[68:71], off offset:256
	v_and_b32_e32 v241, 0xffff0000, v68
	v_lshlrev_b32_e32 v242, 16, v68
	v_mul_f32_e32 v241, v241, v241
	v_fmac_f32_e32 v241, v242, v242
	v_add_f32_e32 v240, v240, v241
	v_and_b32_e32 v241, 0xffff0000, v69
	v_lshlrev_b32_e32 v242, 16, v69
	v_mul_f32_e32 v241, v241, v241
	v_fmac_f32_e32 v241, v242, v242
	v_add_f32_e32 v240, v240, v241
	v_and_b32_e32 v241, 0xffff0000, v70
	v_lshlrev_b32_e32 v242, 16, v70
	v_mul_f32_e32 v241, v241, v241
	v_fmac_f32_e32 v241, v242, v242
	v_add_f32_e32 v240, v240, v241
	v_and_b32_e32 v241, 0xffff0000, v71
	v_lshlrev_b32_e32 v242, 16, v71
	v_mul_f32_e32 v241, v241, v241
	v_fmac_f32_e32 v241, v242, v242
	v_add_f32_e32 v240, v240, v241
	v_lshl_add_u64 v[218:219], v[218:219], 0, s[98:99]
	v_lshl_add_u64 v[218:219], v[218:219], 0, s[98:99]
	v_lshl_add_u64 v[218:219], v[218:219], 0, s[98:99]
	v_lshl_add_u64 v[218:219], v[218:219], 0, s[98:99]
	v_lshl_add_u64 v[218:219], v[218:219], 0, s[98:99]
	v_mov_b32_e32 v244, v240
	s_nop 1
	v_permlane16_swap_b32_e32 v244, v240
	s_nop 1
	v_add_f32_e32 v244, v240, v244
	v_mov_b32_e32 v245, v244
	s_nop 1
	v_permlane32_swap_b32_e32 v245, v244
	s_nop 1
	v_add_f32_e32 v244, v244, v245
	v_mul_f32_e32 v244, 0x49800000, v244
	v_trunc_f32_e32 v244, v244
	v_mul_f32_e32 v245, 0x2f800000, v244
	v_floor_f32_e32 v245, v245
	v_fmac_f32_e32 v244, 0xcf800000, v245
	v_cvt_u32_f32_e32 v245, v245
	v_cvt_u32_f32_e32 v244, v244
	s_and_saveexec_b64 s[10:11], vcc
	global_atomic_add_x2 v[220:221], v[244:245], off offset:384
	s_or_b64 exec, exec, s[10:11]
	s_waitcnt vmcnt(18)
	v_lshlrev_b32_e32 v241, 16, v160
	v_and_b32_e32 v242, 0xffff0000, v160
	v_add_f32_e32 v60, v60, v241
	v_add_f32_e32 v61, v61, v242
	v_lshlrev_b32_e32 v241, 16, v161
	v_and_b32_e32 v242, 0xffff0000, v161
	v_add_f32_e32 v62, v62, v241
	v_add_f32_e32 v63, v63, v242
	v_lshlrev_b32_e32 v241, 16, v162
	v_and_b32_e32 v242, 0xffff0000, v162
	v_add_f32_e32 v56, v56, v241
	v_add_f32_e32 v57, v57, v242
	v_lshlrev_b32_e32 v241, 16, v163
	v_and_b32_e32 v242, 0xffff0000, v163
	v_add_f32_e32 v58, v58, v241
	v_add_f32_e32 v59, v59, v242
	v_cvt_pk_bf16_f32 v60, v60, v61
	v_cvt_pk_bf16_f32 v61, v62, v63
	v_cvt_pk_bf16_f32 v62, v56, v57
	v_cvt_pk_bf16_f32 v63, v58, v59
	global_store_dwordx4 v[218:219], v[60:63], off
	v_and_b32_e32 v241, 0xffff0000, v60
	v_lshlrev_b32_e32 v242, 16, v60
	v_mul_f32_e32 v241, v241, v241
	v_fmac_f32_e32 v241, v242, v242
	v_mov_b32_e32 v240, v241
	v_and_b32_e32 v241, 0xffff0000, v61
	v_lshlrev_b32_e32 v242, 16, v61
	v_mul_f32_e32 v241, v241, v241
	v_fmac_f32_e32 v241, v242, v242
	v_add_f32_e32 v240, v240, v241
	v_and_b32_e32 v241, 0xffff0000, v62
	v_lshlrev_b32_e32 v242, 16, v62
	v_mul_f32_e32 v241, v241, v241
	v_fmac_f32_e32 v241, v242, v242
	v_add_f32_e32 v240, v240, v241
	v_and_b32_e32 v241, 0xffff0000, v63
	v_lshlrev_b32_e32 v242, 16, v63
	v_mul_f32_e32 v241, v241, v241
	v_fmac_f32_e32 v241, v242, v242
	v_add_f32_e32 v240, v240, v241
	v_lshlrev_b32_e32 v241, 16, v164
	v_and_b32_e32 v242, 0xffff0000, v164
	v_add_f32_e32 v52, v52, v241
	v_add_f32_e32 v53, v53, v242
	v_lshlrev_b32_e32 v241, 16, v165
	v_and_b32_e32 v242, 0xffff0000, v165
	v_add_f32_e32 v54, v54, v241
	v_add_f32_e32 v55, v55, v242
	v_lshlrev_b32_e32 v241, 16, v166
	v_and_b32_e32 v242, 0xffff0000, v166
	v_add_f32_e32 v48, v48, v241
	v_add_f32_e32 v49, v49, v242
	v_lshlrev_b32_e32 v241, 16, v167
	v_and_b32_e32 v242, 0xffff0000, v167
	v_add_f32_e32 v50, v50, v241
	v_add_f32_e32 v51, v51, v242
	v_cvt_pk_bf16_f32 v52, v52, v53
	v_cvt_pk_bf16_f32 v53, v54, v55
	v_cvt_pk_bf16_f32 v54, v48, v49
	v_cvt_pk_bf16_f32 v55, v50, v51
	global_store_dwordx4 v[218:219], v[52:55], off offset:256
	v_and_b32_e32 v241, 0xffff0000, v52
	v_lshlrev_b32_e32 v242, 16, v52
	v_mul_f32_e32 v241, v241, v241
	v_fmac_f32_e32 v241, v242, v242
	v_add_f32_e32 v240, v240, v241
	v_and_b32_e32 v241, 0xffff0000, v53
	v_lshlrev_b32_e32 v242, 16, v53
	v_mul_f32_e32 v241, v241, v241
	v_fmac_f32_e32 v241, v242, v242
	v_add_f32_e32 v240, v240, v241
	v_and_b32_e32 v241, 0xffff0000, v54
	v_lshlrev_b32_e32 v242, 16, v54
	v_mul_f32_e32 v241, v241, v241
	v_fmac_f32_e32 v241, v242, v242
	v_add_f32_e32 v240, v240, v241
	v_and_b32_e32 v241, 0xffff0000, v55
	v_lshlrev_b32_e32 v242, 16, v55
	v_mul_f32_e32 v241, v241, v241
	v_fmac_f32_e32 v241, v242, v242
	v_add_f32_e32 v240, v240, v241
	v_lshl_add_u64 v[218:219], v[218:219], 0, s[98:99]
	v_mov_b32_e32 v244, v240
	s_nop 1
	v_permlane16_swap_b32_e32 v244, v240
	s_nop 1
	v_add_f32_e32 v244, v240, v244
	v_mov_b32_e32 v245, v244
	s_nop 1
	v_permlane32_swap_b32_e32 v245, v244
	s_nop 1
	v_add_f32_e32 v244, v244, v245
	v_mul_f32_e32 v244, 0x49800000, v244
	v_trunc_f32_e32 v244, v244
	v_mul_f32_e32 v245, 0x2f800000, v244
	v_floor_f32_e32 v245, v245
	v_fmac_f32_e32 v244, 0xcf800000, v245
	v_cvt_u32_f32_e32 v245, v245
	v_cvt_u32_f32_e32 v244, v244
	s_and_saveexec_b64 s[10:11], vcc
	global_atomic_add_x2 v[220:221], v[244:245], off offset:1024
	s_or_b64 exec, exec, s[10:11]
	s_waitcnt vmcnt(19)
; #define ER_LOAD(q) do { _Pragma("unroll") for (int bj = 0; bj < 2; ++bj) t[(q) & 3][bj] = *(const u32x4*)(base + ER_OFF(q, bj)); } while (0)
; #define ER_ADD(q) do { _Pragma("unroll") for (int bj = 0; bj < 2; ++bj) { f32x4& a0 = acc[(q) >> 2][bj][(q) & 3][0]; f32x4& a1 = acc[(q) >> 2][bj][(q) & 3][1]; const u32x4 p = t[(q) & 3][bj]; \
;             a0[0] += bf_lo(p.x); a0[1] += bf_hi(p.x); a0[2] += bf_lo(p.y); a0[3] += bf_hi(p.y); a1[0] += bf_lo(p.z); a1[1] += bf_hi(p.z); a1[2] += bf_lo(p.w); a1[3] += bf_hi(p.w); } } while (0)
;     __device__ __forceinline__ void operator()(f32x4 (&acc)[2][2][4][2], const Unit& u, int wr, int wc, int fr, int fq) const {
;         const int row0 = u.pm * BM + wr * 64 + fr, col0 = u.pn * BM + wc * 32 + 8 * fq; const unsigned off0 = (unsigned)row0 * 1024u + (unsigned)col0;
;         u32x4 t[4][2];
;     ...
; #pragma unroll
;         for (int q = 0; q < 4; ++q) ER_LOAD(q);
; #pragma unroll
;         for (int q = 0; q < 4; ++q) ER_ADD(q);
; #pragma unroll
;         for (int q = 4; q < 8; ++q) ER_LOAD(q);
; #pragma unroll
;         for (int q = 0; q < 4; ++q) ER_STORE(q);
; #pragma unroll
;         for (int q = 4; q < 8; ++q) { ER_ADD(q); ER_STORE(q); }
	v_lshlrev_b32_e32 v241, 16, v192
	v_and_b32_e32 v242, 0xffff0000, v192
	v_add_f32_e32 v44, v44, v241
	v_add_f32_e32 v45, v45, v242
	v_lshlrev_b32_e32 v241, 16, v193
	v_and_b32_e32 v242, 0xffff0000, v193
	v_add_f32_e32 v46, v46, v241
	v_add_f32_e32 v47, v47, v242
	v_lshlrev_b32_e32 v241, 16, v194
	v_and_b32_e32 v242, 0xffff0000, v194
	v_add_f32_e32 v40, v40, v241
	v_add_f32_e32 v41, v41, v242
	v_lshlrev_b32_e32 v241, 16, v195
	v_and_b32_e32 v242, 0xffff0000, v195
	v_add_f32_e32 v42, v42, v241
	v_add_f32_e32 v43, v43, v242
	v_cvt_pk_bf16_f32 v44, v44, v45
	v_cvt_pk_bf16_f32 v45, v46, v47
	v_cvt_pk_bf16_f32 v46, v40, v41
	v_cvt_pk_bf16_f32 v47, v42, v43
	global_store_dwordx4 v[218:219], v[44:47], off
	v_and_b32_e32 v241, 0xffff0000, v44
	v_lshlrev_b32_e32 v242, 16, v44
	v_mul_f32_e32 v241, v241, v241
	v_fmac_f32_e32 v241, v242, v242
	v_mov_b32_e32 v240, v241
	v_and_b32_e32 v241, 0xffff0000, v45
	v_lshlrev_b32_e32 v242, 16, v45
	v_mul_f32_e32 v241, v241, v241
	v_fmac_f32_e32 v241, v242, v242
	v_add_f32_e32 v240, v240, v241
	v_and_b32_e32 v241, 0xffff0000, v46
	v_lshlrev_b32_e32 v242, 16, v46
	v_mul_f32_e32 v241, v241, v241
	v_fmac_f32_e32 v241, v242, v242
	v_add_f32_e32 v240, v240, v241
	v_and_b32_e32 v241, 0xffff0000, v47
	v_lshlrev_b32_e32 v242, 16, v47
	v_mul_f32_e32 v241, v241, v241
	v_fmac_f32_e32 v241, v242, v242
	v_add_f32_e32 v240, v240, v241
	v_lshlrev_b32_e32 v241, 16, v196
	v_and_b32_e32 v242, 0xffff0000, v196
	v_add_f32_e32 v36, v36, v241
	v_add_f32_e32 v37, v37, v242
	v_lshlrev_b32_e32 v241, 16, v197
	v_and_b32_e32 v242, 0xffff0000, v197
	v_add_f32_e32 v38, v38, v241
	v_add_f32_e32 v39, v39, v242
	v_lshlrev_b32_e32 v241, 16, v198
	v_and_b32_e32 v242, 0xffff0000, v198
	v_add_f32_e32 v32, v32, v241
	v_add_f32_e32 v33, v33, v242
	v_lshlrev_b32_e32 v241, 16, v199
	v_and_b32_e32 v242, 0xffff0000, v199
	v_add_f32_e32 v34, v34, v241
	v_add_f32_e32 v35, v35, v242
	v_cvt_pk_bf16_f32 v36, v36, v37
	v_cvt_pk_bf16_f32 v37, v38, v39
	v_cvt_pk_bf16_f32 v38, v32, v33
	v_cvt_pk_bf16_f32 v39, v34, v35
	global_store_dwordx4 v[218:219], v[36:39], off offset:256
	v_and_b32_e32 v241, 0xffff0000, v36
	v_lshlrev_b32_e32 v242, 16, v36
	v_mul_f32_e32 v241, v241, v241
	v_fmac_f32_e32 v241, v242, v242
	v_add_f32_e32 v240, v240, v241
	v_and_b32_e32 v241, 0xffff0000, v37
	v_lshlrev_b32_e32 v242, 16, v37
	v_mul_f32_e32 v241, v241, v241
	v_fmac_f32_e32 v241, v242, v242
	v_add_f32_e32 v240, v240, v241
	v_and_b32_e32 v241, 0xffff0000, v38
	v_lshlrev_b32_e32 v242, 16, v38
	v_mul_f32_e32 v241, v241, v241
	v_fmac_f32_e32 v241, v242, v242
	v_add_f32_e32 v240, v240, v241
	v_and_b32_e32 v241, 0xffff0000, v39
	v_lshlrev_b32_e32 v242, 16, v39
	v_mul_f32_e32 v241, v241, v241
	v_fmac_f32_e32 v241, v242, v242
	v_add_f32_e32 v240, v240, v241
	v_lshl_add_u64 v[218:219], v[218:219], 0, s[98:99]
	v_mov_b32_e32 v244, v240
	s_nop 1
	v_permlane16_swap_b32_e32 v244, v240
	s_nop 1
	v_add_f32_e32 v244, v240, v244
	v_mov_b32_e32 v245, v244
	s_nop 1
	v_permlane32_swap_b32_e32 v245, v244
	s_nop 1
	v_add_f32_e32 v244, v244, v245
	v_mul_f32_e32 v244, 0x49800000, v244
	v_trunc_f32_e32 v244, v244
	v_mul_f32_e32 v245, 0x2f800000, v244
	v_floor_f32_e32 v245, v245
	v_fmac_f32_e32 v244, 0xcf800000, v245
	v_cvt_u32_f32_e32 v245, v245
	v_cvt_u32_f32_e32 v244, v244
	s_and_saveexec_b64 s[10:11], vcc
	global_atomic_add_x2 v[220:221], v[244:245], off offset:1152
	s_or_b64 exec, exec, s[10:11]
	s_waitcnt vmcnt(20)
; #define ER_LOAD(q) do { _Pragma("unroll") for (int bj = 0; bj < 2; ++bj) t[(q) & 3][bj] = *(const u32x4*)(base + ER_OFF(q, bj)); } while (0)
; #define ER_ADD(q) do { _Pragma("unroll") for (int bj = 0; bj < 2; ++bj) { f32x4& a0 = acc[(q) >> 2][bj][(q) & 3][0]; f32x4& a1 = acc[(q) >> 2][bj][(q) & 3][1]; const u32x4 p = t[(q) & 3][bj]; \
;             a0[0] += bf_lo(p.x); a0[1] += bf_hi(p.x); a0[2] += bf_lo(p.y); a0[3] += bf_hi(p.y); a1[0] += bf_lo(p.z); a1[1] += bf_hi(p.z); a1[2] += bf_lo(p.w); a1[3] += bf_hi(p.w); } } while (0)
;     __device__ __forceinline__ void operator()(f32x4 (&acc)[2][2][4][2], const Unit& u, int wr, int wc, int fr, int fq) const {
;         const int row0 = u.pm * BM + wr * 64 + fr, col0 = u.pn * BM + wc * 32 + 8 * fq; const unsigned off0 = (unsigned)row0 * 1024u + (unsigned)col0;
;         u32x4 t[4][2];
;     ...
; #pragma unroll
;         for (int q = 0; q < 4; ++q) ER_LOAD(q);
; #pragma unroll
;         for (int q = 0; q < 4; ++q) ER_ADD(q);
; #pragma unroll
;         for (int q = 4; q < 8; ++q) ER_LOAD(q);
; #pragma unroll
;         for (int q = 0; q < 4; ++q) ER_STORE(q);
; #pragma unroll
;         for (int q = 4; q < 8; ++q) { ER_ADD(q); ER_STORE(q); }
	v_lshlrev_b32_e32 v241, 16, v200
	v_and_b32_e32 v242, 0xffff0000, v200
	v_add_f32_e32 v28, v28, v241
	v_add_f32_e32 v29, v29, v242
	v_lshlrev_b32_e32 v241, 16, v201
	v_and_b32_e32 v242, 0xffff0000, v201
	v_add_f32_e32 v30, v30, v241
	v_add_f32_e32 v31, v31, v242
	v_lshlrev_b32_e32 v241, 16, v202
	v_and_b32_e32 v242, 0xffff0000, v202
	v_add_f32_e32 v24, v24, v241
	v_add_f32_e32 v25, v25, v242
	v_lshlrev_b32_e32 v241, 16, v203
	v_and_b32_e32 v242, 0xffff0000, v203
	v_add_f32_e32 v26, v26, v241
	v_add_f32_e32 v27, v27, v242
	v_cvt_pk_bf16_f32 v28, v28, v29
	v_cvt_pk_bf16_f32 v29, v30, v31
	v_cvt_pk_bf16_f32 v30, v24, v25
	v_cvt_pk_bf16_f32 v31, v26, v27
	global_store_dwordx4 v[218:219], v[28:31], off
	v_and_b32_e32 v241, 0xffff0000, v28
	v_lshlrev_b32_e32 v242, 16, v28
	v_mul_f32_e32 v241, v241, v241
	v_fmac_f32_e32 v241, v242, v242
	v_mov_b32_e32 v240, v241
	v_and_b32_e32 v241, 0xffff0000, v29
	v_lshlrev_b32_e32 v242, 16, v29
	v_mul_f32_e32 v241, v241, v241
	v_fmac_f32_e32 v241, v242, v242
	v_add_f32_e32 v240, v240, v241
	v_and_b32_e32 v241, 0xffff0000, v30
	v_lshlrev_b32_e32 v242, 16, v30
	v_mul_f32_e32 v241, v241, v241
	v_fmac_f32_e32 v241, v242, v242
	v_add_f32_e32 v240, v240, v241
	v_and_b32_e32 v241, 0xffff0000, v31
	v_lshlrev_b32_e32 v242, 16, v31
	v_mul_f32_e32 v241, v241, v241
	v_fmac_f32_e32 v241, v242, v242
	v_add_f32_e32 v240, v240, v241
	v_lshlrev_b32_e32 v241, 16, v204
	v_and_b32_e32 v242, 0xffff0000, v204
	v_add_f32_e32 v20, v20, v241
	v_add_f32_e32 v21, v21, v242
	v_lshlrev_b32_e32 v241, 16, v205
	v_and_b32_e32 v242, 0xffff0000, v205
	v_add_f32_e32 v22, v22, v241
	v_add_f32_e32 v23, v23, v242
	v_lshlrev_b32_e32 v241, 16, v206
	v_and_b32_e32 v242, 0xffff0000, v206
	v_add_f32_e32 v16, v16, v241
	v_add_f32_e32 v17, v17, v242
	v_lshlrev_b32_e32 v241, 16, v207
	v_and_b32_e32 v242, 0xffff0000, v207
	v_add_f32_e32 v18, v18, v241
	v_add_f32_e32 v19, v19, v242
	v_cvt_pk_bf16_f32 v20, v20, v21
	v_cvt_pk_bf16_f32 v21, v22, v23
	v_cvt_pk_bf16_f32 v22, v16, v17
	v_cvt_pk_bf16_f32 v23, v18, v19
	global_store_dwordx4 v[218:219], v[20:23], off offset:256
	v_and_b32_e32 v241, 0xffff0000, v20
	v_lshlrev_b32_e32 v242, 16, v20
	v_mul_f32_e32 v241, v241, v241
	v_fmac_f32_e32 v241, v242, v242
	v_add_f32_e32 v240, v240, v241
	v_and_b32_e32 v241, 0xffff0000, v21
	v_lshlrev_b32_e32 v242, 16, v21
	v_mul_f32_e32 v241, v241, v241
	v_fmac_f32_e32 v241, v242, v242
	v_add_f32_e32 v240, v240, v241
	v_and_b32_e32 v241, 0xffff0000, v22
	v_lshlrev_b32_e32 v242, 16, v22
	v_mul_f32_e32 v241, v241, v241
	v_fmac_f32_e32 v241, v242, v242
	v_add_f32_e32 v240, v240, v241
	v_and_b32_e32 v241, 0xffff0000, v23
	v_lshlrev_b32_e32 v242, 16, v23
	v_mul_f32_e32 v241, v241, v241
	v_fmac_f32_e32 v241, v242, v242
	v_add_f32_e32 v240, v240, v241
	v_lshl_add_u64 v[218:219], v[218:219], 0, s[98:99]
	v_mov_b32_e32 v244, v240
	s_nop 1
	v_permlane16_swap_b32_e32 v244, v240
	s_nop 1
	v_add_f32_e32 v244, v240, v244
	v_mov_b32_e32 v245, v244
	s_nop 1
	v_permlane32_swap_b32_e32 v245, v244
	s_nop 1
	v_add_f32_e32 v244, v244, v245
	v_mul_f32_e32 v244, 0x49800000, v244
	v_trunc_f32_e32 v244, v244
	v_mul_f32_e32 v245, 0x2f800000, v244
	v_floor_f32_e32 v245, v245
	v_fmac_f32_e32 v244, 0xcf800000, v245
	v_cvt_u32_f32_e32 v245, v245
	v_cvt_u32_f32_e32 v244, v244
	s_and_saveexec_b64 s[10:11], vcc
	global_atomic_add_x2 v[220:221], v[244:245], off offset:1280
	s_or_b64 exec, exec, s[10:11]
	s_waitcnt vmcnt(21)
	v_lshlrev_b32_e32 v241, 16, v208
	v_and_b32_e32 v242, 0xffff0000, v208
	v_add_f32_e32 v12, v12, v241
	v_add_f32_e32 v13, v13, v242
	v_lshlrev_b32_e32 v241, 16, v209
	v_and_b32_e32 v242, 0xffff0000, v209
	v_add_f32_e32 v14, v14, v241
	v_add_f32_e32 v15, v15, v242
	v_lshlrev_b32_e32 v241, 16, v210
	v_and_b32_e32 v242, 0xffff0000, v210
	v_add_f32_e32 v8, v8, v241
	v_add_f32_e32 v9, v9, v242
	v_lshlrev_b32_e32 v241, 16, v211
	v_and_b32_e32 v242, 0xffff0000, v211
	v_add_f32_e32 v10, v10, v241
	v_add_f32_e32 v11, v11, v242
	v_cvt_pk_bf16_f32 v12, v12, v13
	v_cvt_pk_bf16_f32 v13, v14, v15
	v_cvt_pk_bf16_f32 v14, v8, v9
	v_cvt_pk_bf16_f32 v15, v10, v11
	global_store_dwordx4 v[218:219], v[12:15], off
	v_and_b32_e32 v241, 0xffff0000, v12
	v_lshlrev_b32_e32 v242, 16, v12
	v_mul_f32_e32 v241, v241, v241
	v_fmac_f32_e32 v241, v242, v242
	v_mov_b32_e32 v240, v241
	v_and_b32_e32 v241, 0xffff0000, v13
	v_lshlrev_b32_e32 v242, 16, v13
	v_mul_f32_e32 v241, v241, v241
	v_fmac_f32_e32 v241, v242, v242
	v_add_f32_e32 v240, v240, v241
	v_and_b32_e32 v241, 0xffff0000, v14
	v_lshlrev_b32_e32 v242, 16, v14
	v_mul_f32_e32 v241, v241, v241
	v_fmac_f32_e32 v241, v242, v242
	v_add_f32_e32 v240, v240, v241
	v_and_b32_e32 v241, 0xffff0000, v15
	v_lshlrev_b32_e32 v242, 16, v15
	v_mul_f32_e32 v241, v241, v241
	v_fmac_f32_e32 v241, v242, v242
	v_add_f32_e32 v240, v240, v241
	v_lshlrev_b32_e32 v241, 16, v212
	v_and_b32_e32 v242, 0xffff0000, v212
	v_add_f32_e32 v4, v4, v241
	v_add_f32_e32 v5, v5, v242
	v_lshlrev_b32_e32 v241, 16, v213
	v_and_b32_e32 v242, 0xffff0000, v213
	v_add_f32_e32 v6, v6, v241
	v_add_f32_e32 v7, v7, v242
	v_lshlrev_b32_e32 v241, 16, v214
	v_and_b32_e32 v242, 0xffff0000, v214
	v_add_f32_e32 v0, v0, v241
	v_add_f32_e32 v1, v1, v242
	v_lshlrev_b32_e32 v241, 16, v215
	v_and_b32_e32 v242, 0xffff0000, v215
	v_add_f32_e32 v2, v2, v241
	v_add_f32_e32 v3, v3, v242
	v_cvt_pk_bf16_f32 v4, v4, v5
	v_cvt_pk_bf16_f32 v5, v6, v7
	v_cvt_pk_bf16_f32 v6, v0, v1
	v_cvt_pk_bf16_f32 v7, v2, v3
	global_store_dwordx4 v[218:219], v[4:7], off offset:256
	v_and_b32_e32 v241, 0xffff0000, v4
	v_lshlrev_b32_e32 v242, 16, v4
	v_mul_f32_e32 v241, v241, v241
	v_fmac_f32_e32 v241, v242, v242
	v_add_f32_e32 v240, v240, v241
	v_and_b32_e32 v241, 0xffff0000, v5
	v_lshlrev_b32_e32 v242, 16, v5
	v_mul_f32_e32 v241, v241, v241
	v_fmac_f32_e32 v241, v242, v242
	v_add_f32_e32 v240, v240, v241
	v_and_b32_e32 v241, 0xffff0000, v6
	v_lshlrev_b32_e32 v242, 16, v6
	v_mul_f32_e32 v241, v241, v241
	v_fmac_f32_e32 v241, v242, v242
	v_add_f32_e32 v240, v240, v241
	v_and_b32_e32 v241, 0xffff0000, v7
	v_lshlrev_b32_e32 v242, 16, v7
	v_mul_f32_e32 v241, v241, v241
	v_fmac_f32_e32 v241, v242, v242
	v_add_f32_e32 v240, v240, v241
	v_mov_b32_e32 v244, v240
	s_nop 1
	v_permlane16_swap_b32_e32 v244, v240
	s_nop 1
	v_add_f32_e32 v244, v240, v244
	v_mov_b32_e32 v245, v244
	s_nop 1
	v_permlane32_swap_b32_e32 v245, v244
	s_nop 1
	v_add_f32_e32 v244, v244, v245
	v_mul_f32_e32 v244, 0x49800000, v244
	v_trunc_f32_e32 v244, v244
	v_mul_f32_e32 v245, 0x2f800000, v244
	v_floor_f32_e32 v245, v245
	v_fmac_f32_e32 v244, 0xcf800000, v245
	v_cvt_u32_f32_e32 v245, v245
	v_cvt_u32_f32_e32 v244, v244
	s_and_saveexec_b64 s[10:11], vcc
	global_atomic_add_x2 v[220:221], v[244:245], off offset:1408
	s_or_b64 exec, exec, s[10:11]
	s_mov_b64 s[10:11], exec
	s_branch .LBB0_265
